# gather_u fetch: row validity from a scalar remaining-row counter (one VALU fewer per row group)
# speedup vs baseline: 1.0023x; 1.0023x over previous
; __device__ void phase_gather_u(const Params& p) {
;   const int tid = threadIdx.x, lane = tid & 63, wid = tid >> 6;
;   unsigned char* ws = p.ws;
;   const unsigned char* ub = ws + OFF_XB;
;   const int* idxg = (const int*)(ws + OFF_IDX);
;   u32x4* xq = (u32x4*)(ws + OFF_XQ);
;   int* wbuf = (int*)(ws + OFF_WBUF);
;   float* sxa = (float*)(ws + OFF_WBUF + 8 * MIB);
;   const bool b5 = (lane & 32) != 0, b4 = (lane & 16) != 0, b3 = (lane & 8) != 0;
;   const int srcl = ((lane & 1) << 3) | (((lane >> 1) & 1) << 4) | (((lane >> 2) & 1) << 5);
;   const int tbase = blockIdx.x * 8 + wid, tstride = gridDim.x * 8;
;   for (int t = tbase; t < T_TOK; t += tstride) {
;     ...
;     for (int t = tbase; t < T_TOK; t += tstride) {
;       const u32x4 ph = xq[((size_t)t * 64 + lane) * 2], pl = xq[((size_t)t * 64 + lane) * 2 + 1];
;       const int idA = idxg[(size_t)t * 128 + lane], idB = idxg[(size_t)t * 128 + 64 + lane];
.LBB0_1205:
	s_or_b64 exec, exec, s[4:5]
	v_and_b32_e32 v0, 32, v139
	v_cmp_eq_u32_e64 s[2:3], 0, v0
	v_and_b32_e32 v0, 16, v139
	v_cmp_eq_u32_e64 s[4:5], 0, v0
	v_and_b32_e32 v0, 8, v139
	s_add_u32 s10, s34, 0xc000000
	v_cmp_eq_u32_e64 s[6:7], 0, v0
	v_mov_b32_e32 v1, 0
	v_lshlrev_b32_e32 v0, 5, v138
	s_addc_u32 s11, s35, 0
	s_waitcnt lgkmcnt(0)
	v_lshl_add_u64 v[2:3], s[34:35], 0, v[0:1]
	v_lshlrev_b32_e32 v0, 2, v138
	v_lshlrev_b32_e32 v82, 3, v139
	v_writelane_b32 v250, s10, 18
	v_mbcnt_hi_u32_b32 v83, -1, v30
	v_and_b32_e32 v4, 56, v82
	v_lshl_add_u64 v[76:77], s[10:11], 0, v[0:1]
	v_lshlrev_b32_e32 v0, 4, v138
	s_waitcnt vmcnt(0)
	v_lshl_add_u64 v[72:73], s[34:35], 0, v[0:1]
	v_and_b32_e32 v0, 64, v83
	s_add_u32 s70, s34, 0x17400000
	s_mov_b64 s[8:9], 0x15400000
	v_add_u32_e32 v84, 64, v0
	v_or_b32_e32 v0, v0, v4
	s_addc_u32 s71, s35, 0
	s_mov_b32 s33, 0
	v_lshl_add_u64 v[74:75], v[2:3], 0, s[8:9]
	v_writelane_b32 v250, s11, 19
	v_cmp_gt_u32_e64 s[8:9], 8, v138
	v_cmp_eq_u32_e64 s[10:11], 1, v138
	v_cmp_eq_u32_e64 s[12:13], 2, v138
	v_cmp_eq_u32_e64 s[14:15], 3, v138
	v_cmp_eq_u32_e64 s[16:17], 4, v138
	v_cmp_eq_u32_e64 s[18:19], 5, v138
	v_cmp_eq_u32_e64 s[20:21], 6, v138
	v_cmp_eq_u32_e64 s[22:23], 7, v138
	s_movk_i32 s48, 0x3fff
	v_xor_b32_e32 v89, 32, v83
	v_xor_b32_e32 v90, 16, v83
	v_xor_b32_e32 v88, 8, v83
	v_xor_b32_e32 v87, 4, v83
	v_xor_b32_e32 v86, 2, v83
	v_xor_b32_e32 v85, 1, v83
	v_lshlrev_b32_e32 v91, 2, v0
	v_and_b32_e32 v96, 15, v138
	v_lshrrev_b32_e32 v99, 4, v138
	v_lshlrev_b32_e32 v98, 2, v138
	v_lshrrev_b32_e32 v100, 6, v139
	v_cmp_eq_u32_e64 s[8:9], 0, v96
	v_lshlrev_b32_e32 v97, 5, v96
	v_lshlrev_b32_e32 v96, 4, v96
	v_readfirstlane_b32 s60, v100
	v_readfirstlane_b32 s61, v112
	s_add_u32 s64, s34, 0x15400000
	s_addc_u32 s65, s35, 0
	s_add_u32 s62, s34, 0xc000000
	s_addc_u32 s63, s35, 0
	s_lshl_b32 s60, s60, 10
	s_and_saveexec_b64 s[38:39], s[0:1]
	s_cbranch_execz .Lgu_done
	s_mov_b32 s33, 0
	s_mov_b32 s66, 0
	s_lshl_b32 s40, s61, 9
	s_add_u32 s40, s62, s40
	s_addc_u32 s41, s63, 0
	s_lshl_b32 s46, s61, 11
	s_add_u32 s46, s64, s46
	s_addc_u32 s47, s65, 0
	global_load_dword v94, v98, s[40:41]
	global_load_dword v95, v98, s[40:41] offset:256
	global_load_dwordx4 v[168:171], v97, s[46:47]
	global_load_dwordx4 v[172:175], v97, s[46:47] offset:16
	global_load_dwordx4 v[176:179], v97, s[46:47] offset:512
	global_load_dwordx4 v[180:183], v97, s[46:47] offset:528
	global_load_dwordx4 v[184:187], v97, s[46:47] offset:1024
	global_load_dwordx4 v[188:191], v97, s[46:47] offset:1040
	global_load_dwordx4 v[192:195], v97, s[46:47] offset:1536
	global_load_dwordx4 v[196:199], v97, s[46:47] offset:1552
	s_add_i32 s37, s61, s68
	s_lshl_b32 s40, s37, 9
	s_add_u32 s40, s62, s40
	s_addc_u32 s41, s63, 0
	s_lshl_b32 s46, s37, 11
	s_add_u32 s46, s64, s46
	s_addc_u32 s47, s65, 0
	global_load_dword v232, v98, s[40:41]
	global_load_dword v233, v98, s[40:41] offset:256
	global_load_dwordx4 v[200:203], v97, s[46:47]
	global_load_dwordx4 v[204:207], v97, s[46:47] offset:16
	global_load_dwordx4 v[208:211], v97, s[46:47] offset:512
	global_load_dwordx4 v[212:215], v97, s[46:47] offset:528
	global_load_dwordx4 v[216:219], v97, s[46:47] offset:1024
	global_load_dwordx4 v[220:223], v97, s[46:47] offset:1040
	global_load_dwordx4 v[224:227], v97, s[46:47] offset:1536
	global_load_dwordx4 v[228:231], v97, s[46:47] offset:1552
	s_mov_b32 s67, 0xfffc00

; __device__ void phase_gather_u(const Params& p) {
;     ...
;       unsigned long long m0 = __ballot((idA >> 12) == r), m1 = __ballot((idB >> 12) == r);
;       while (m0 | m1) {
;         int jk[16];
;         u32x4 rw[16];
;         const int nvalid = min((int)(__popcll(m0) + __popcll(m1)), 16);
;         int jfirst, efirst;
;         if (m0) { jfirst = __builtin_amdgcn_readfirstlane(__ffsll((long long)m0) - 1); efirst = __builtin_amdgcn_readlane(idA, jfirst); }
;         else { const int j1 = __builtin_amdgcn_readfirstlane(__ffsll((long long)m1) - 1); efirst = __builtin_amdgcn_readlane(idB, j1); jfirst = 64 + j1; }
; #pragma unroll
;         for (int k = 0; k < 16; ++k) {
;           int j = jfirst, e = efirst;
;           if (m0) { const int jj = __builtin_amdgcn_readfirstlane(__ffsll((long long)m0) - 1); m0 &= m0 - 1ull; j = jj; e = __builtin_amdgcn_readlane(idA, jj); }
;           else if (m1) { const int jj = __builtin_amdgcn_readfirstlane(__ffsll((long long)m1) - 1); m1 &= m1 - 1ull; j = 64 + jj; e = __builtin_amdgcn_readlane(idB, jj); }
;           jk[k] = j;
;           rw[k] = *(const u32x4*)(ub + (size_t)e * 1024 + lane * 16);
.Lgu_cpdone:
	v_lshrrev_b32_e32 v103, 12, v92
	v_lshrrev_b32_e32 v104, 12, v93
	v_cmp_eq_u32_e64 s[44:45], s33, v103
	v_cmp_eq_u32_e64 s[42:43], s33, v104
	s_nop 3
	s_bcnt1_i32_b64 s59, s[44:45]
	s_bcnt1_i32_b64 s56, s[42:43]
	s_add_i32 s56, s56, s59
	s_cmp_eq_u32 s56, 0
	s_cbranch_scc1 .Lgu_tnext
	v_mbcnt_lo_u32_b32 v114, s44, 0
	v_mbcnt_hi_u32_b32 v114, s45, v114
	v_mbcnt_lo_u32_b32 v111, s42, 0
	v_mbcnt_hi_u32_b32 v111, s43, v111
	v_lshl_add_u32 v113, v92, 10, v98
	v_lshl_add_u32 v100, v114, 2, s60
	v_add_u32_e32 v111, s59, v111
	s_mov_b64 exec, s[44:45]
	ds_write_b32 v100, v113
	s_mov_b64 exec, -1
	v_add_u32_e32 v113, 0x100, v98
	v_lshl_add_u32 v100, v111, 2, s60
	v_lshl_add_u32 v113, v93, 10, v113
	s_mov_b64 exec, s[42:43]
	ds_write_b32 v100, v113
	s_mov_b64 exec, -1
	s_add_i32 s57, s56, 3
	s_lshr_b32 s57, s57, 2
	v_lshl_add_u32 v101, v99, 2, s60
	s_mov_b32 s59, s56
	s_mov_b32 s58, 0
	ds_read_b32 v115, v101
	v_add_u32_e32 v101, 16, v101
	s_waitcnt lgkmcnt(0)
	ds_read_b32 v116, v101
	v_cmp_gt_u32_e64 s[50:51], s59, v99
	v_add_u32_e32 v101, 16, v101
	s_sub_i32 s59, s59, 4
	s_max_i32 s59, s59, 0
	v_cndmask_b32_e64 v103, 0, v115, s[50:51]
	v_and_or_b32 v104, v103, s67, v96
	v_and_b32_e32 v105, 0x3ff, v103
	s_and_b64 s[50:51], s[50:51], s[8:9]
	global_load_dwordx4 v[32:35], v104, s[34:35]
	global_load_dwordx4 v[36:39], v104, s[34:35] offset:256
	global_load_dwordx4 v[40:43], v104, s[34:35] offset:512
	global_load_dwordx4 v[44:47], v104, s[34:35] offset:768
	s_waitcnt lgkmcnt(0)
	ds_read_b32 v117, v101
	v_cmp_gt_u32_e64 s[52:53], s59, v99
	v_add_u32_e32 v101, 16, v101
	s_sub_i32 s59, s59, 4
	s_max_i32 s59, s59, 0
	v_cndmask_b32_e64 v103, 0, v116, s[52:53]
	v_and_or_b32 v104, v103, s67, v96
	v_and_b32_e32 v106, 0x3ff, v103
	s_and_b64 s[52:53], s[52:53], s[8:9]
	global_load_dwordx4 v[48:51], v104, s[34:35]
	global_load_dwordx4 v[52:55], v104, s[34:35] offset:256
	global_load_dwordx4 v[56:59], v104, s[34:35] offset:512
	global_load_dwordx4 v[60:63], v104, s[34:35] offset:768
; __device__ void phase_gather_u(const Params& p) {
;     ...
; #pragma unroll
;         for (int k = 0; k < 16; ++k) {
;           int j = jfirst, e = efirst;
;           if (m0) { const int jj = __builtin_amdgcn_readfirstlane(__ffsll((long long)m0) - 1); m0 &= m0 - 1ull; j = jj; e = __builtin_amdgcn_readlane(idA, jj); }
;           else if (m1) { const int jj = __builtin_amdgcn_readfirstlane(__ffsll((long long)m1) - 1); m1 &= m1 - 1ull; j = 64 + jj; e = __builtin_amdgcn_readlane(idB, jj); }
;           jk[k] = j;
;           rw[k] = *(const u32x4*)(ub + (size_t)e * 1024 + lane * 16);
;         }
; #pragma unroll
;         for (int bt = 0; bt < 2; ++bt) {
;           int dv[8];
; #pragma unroll
;           for (int k = 0; k < 8; ++k) {
;             int dh = 0, dl = 0;
; #pragma unroll
;             for (int q = 0; q < 4; ++q) {
;               dh = __builtin_amdgcn_sdot8((int)rw[bt * 8 + k][q], (int)ph[q], dh, false);
;               dl = __builtin_amdgcn_sdot8((int)rw[bt * 8 + k][q], (int)pl[q], dl, false);
;             }
;             dv[k] = 16 * dh + dl;
;           }
;           int a4[4], a2[2];
; #pragma unroll
;           for (int k = 0; k < 4; ++k) {
;             const int mine = b5 ? dv[k + 4] : dv[k], oth = b5 ? dv[k] : dv[k + 4];
;             a4[k] = mine + __shfl_xor(oth, 32);
;           }
; #pragma unroll
;           for (int k = 0; k < 2; ++k) {
;             const int mine = b4 ? a4[k + 2] : a4[k], oth = b4 ? a4[k] : a4[k + 2];
;             a2[k] = mine + __shfl_xor(oth, 16);
;           }
;           int c1;
;           {
;             const int mine = b3 ? a2[1] : a2[0], oth = b3 ? a2[0] : a2[1];
;             c1 = mine + __shfl_xor(oth, 8);
;           }
;           c1 += __shfl_xor(c1, 4);
;           c1 += __shfl_xor(c1, 2);
;           c1 += __shfl_xor(c1, 1);
;           const int val = __shfl(c1, srcl);
;           int jsel = jk[bt * 8];
; #pragma unroll
;           for (int k = 1; k < 8; ++k) jsel = (lane == k) ? jk[bt * 8 + k] : jsel;
;           if (lane < 8 && lane < nvalid - bt * 8) wbuf[(size_t)t * 128 + jsel] = val;
.Lgu_gloop:
	s_waitcnt lgkmcnt(0)
	ds_read_b32 v115, v101
	v_cmp_gt_u32_e64 s[54:55], s59, v99
	v_add_u32_e32 v101, 16, v101
	s_sub_i32 s59, s59, 4
	s_max_i32 s59, s59, 0
	v_cndmask_b32_e64 v103, 0, v117, s[54:55]
	v_and_or_b32 v104, v103, s67, v96
	v_and_b32_e32 v107, 0x3ff, v103
	s_and_b64 s[54:55], s[54:55], s[8:9]
	global_load_dwordx4 v[144:147], v104, s[34:35]
	global_load_dwordx4 v[148:151], v104, s[34:35] offset:256
	global_load_dwordx4 v[152:155], v104, s[34:35] offset:512
	global_load_dwordx4 v[156:159], v104, s[34:35] offset:768
	s_waitcnt vmcnt(8)
	v_mov_b32_e32 v108, 0
	v_mov_b32_e32 v109, 0
	s_nop 1
	v_dot8c_i32_i4_e32 v108, v32, v0
	v_dot8c_i32_i4_e32 v109, v32, v4
	v_dot8c_i32_i4_e32 v108, v33, v1
	v_dot8c_i32_i4_e32 v109, v33, v5
	v_dot8c_i32_i4_e32 v108, v34, v2
	v_dot8c_i32_i4_e32 v109, v34, v6
	v_dot8c_i32_i4_e32 v108, v35, v3
	v_dot8c_i32_i4_e32 v109, v35, v7
	v_dot8c_i32_i4_e32 v108, v36, v8
	v_dot8c_i32_i4_e32 v109, v36, v12
	v_dot8c_i32_i4_e32 v108, v37, v9
	v_dot8c_i32_i4_e32 v109, v37, v13
	v_dot8c_i32_i4_e32 v108, v38, v10
	v_dot8c_i32_i4_e32 v109, v38, v14
	v_dot8c_i32_i4_e32 v108, v39, v11
	v_dot8c_i32_i4_e32 v109, v39, v15
	v_dot8c_i32_i4_e32 v108, v40, v16
	v_dot8c_i32_i4_e32 v109, v40, v20
	v_dot8c_i32_i4_e32 v108, v41, v17
	v_dot8c_i32_i4_e32 v109, v41, v21
	v_dot8c_i32_i4_e32 v108, v42, v18
	v_dot8c_i32_i4_e32 v109, v42, v22
	v_dot8c_i32_i4_e32 v108, v43, v19
	v_dot8c_i32_i4_e32 v109, v43, v23
	v_dot8c_i32_i4_e32 v108, v44, v24
	v_dot8c_i32_i4_e32 v109, v44, v28
	v_dot8c_i32_i4_e32 v108, v45, v25
	v_dot8c_i32_i4_e32 v109, v45, v29
	v_dot8c_i32_i4_e32 v108, v46, v26
	v_dot8c_i32_i4_e32 v109, v46, v30
	v_dot8c_i32_i4_e32 v108, v47, v27
	v_dot8c_i32_i4_e32 v109, v47, v31
	s_nop 2
	v_lshl_add_u32 v110, v108, 4, v109
	s_nop 1
	v_add_u32_dpp v110, v110, v110 quad_perm:[1,0,3,2] row_mask:0xf bank_mask:0xf
	s_nop 1
	v_add_u32_dpp v110, v110, v110 quad_perm:[2,3,0,1] row_mask:0xf bank_mask:0xf
	s_nop 1
	v_add_u32_dpp v110, v110, v110 row_half_mirror row_mask:0xf bank_mask:0xf
	s_nop 1
	v_add_u32_dpp v110, v110, v110 row_mirror row_mask:0xf bank_mask:0xf
	s_mov_b64 exec, s[50:51]
	global_store_dword v105, v110, s[48:49]
	s_mov_b64 exec, -1
	s_add_i32 s58, s58, 1
	s_cmp_ge_u32 s58, s57
	s_cbranch_scc1 .Lgu_tnext
	s_waitcnt lgkmcnt(0)
	ds_read_b32 v116, v101
	v_cmp_gt_u32_e64 s[50:51], s59, v99
	v_add_u32_e32 v101, 16, v101
	s_sub_i32 s59, s59, 4
	s_max_i32 s59, s59, 0
	v_cndmask_b32_e64 v103, 0, v115, s[50:51]
	v_and_or_b32 v104, v103, s67, v96
	v_and_b32_e32 v105, 0x3ff, v103
	s_and_b64 s[50:51], s[50:51], s[8:9]
	global_load_dwordx4 v[32:35], v104, s[34:35]
	global_load_dwordx4 v[36:39], v104, s[34:35] offset:256
	global_load_dwordx4 v[40:43], v104, s[34:35] offset:512
	global_load_dwordx4 v[44:47], v104, s[34:35] offset:768
	s_waitcnt vmcnt(8)
	v_mov_b32_e32 v108, 0
	v_mov_b32_e32 v109, 0
	s_nop 1
	v_dot8c_i32_i4_e32 v108, v48, v0
	v_dot8c_i32_i4_e32 v109, v48, v4
	v_dot8c_i32_i4_e32 v108, v49, v1
	v_dot8c_i32_i4_e32 v109, v49, v5
	v_dot8c_i32_i4_e32 v108, v50, v2
	v_dot8c_i32_i4_e32 v109, v50, v6
	v_dot8c_i32_i4_e32 v108, v51, v3
	v_dot8c_i32_i4_e32 v109, v51, v7
	v_dot8c_i32_i4_e32 v108, v52, v8
	v_dot8c_i32_i4_e32 v109, v52, v12
	v_dot8c_i32_i4_e32 v108, v53, v9
	v_dot8c_i32_i4_e32 v109, v53, v13
	v_dot8c_i32_i4_e32 v108, v54, v10
	v_dot8c_i32_i4_e32 v109, v54, v14
	v_dot8c_i32_i4_e32 v108, v55, v11
	v_dot8c_i32_i4_e32 v109, v55, v15
	v_dot8c_i32_i4_e32 v108, v56, v16
	v_dot8c_i32_i4_e32 v109, v56, v20
	v_dot8c_i32_i4_e32 v108, v57, v17
	v_dot8c_i32_i4_e32 v109, v57, v21
	v_dot8c_i32_i4_e32 v108, v58, v18
	v_dot8c_i32_i4_e32 v109, v58, v22
	v_dot8c_i32_i4_e32 v108, v59, v19
	v_dot8c_i32_i4_e32 v109, v59, v23
	v_dot8c_i32_i4_e32 v108, v60, v24
	v_dot8c_i32_i4_e32 v109, v60, v28
	v_dot8c_i32_i4_e32 v108, v61, v25
	v_dot8c_i32_i4_e32 v109, v61, v29
	v_dot8c_i32_i4_e32 v108, v62, v26
	v_dot8c_i32_i4_e32 v109, v62, v30
	v_dot8c_i32_i4_e32 v108, v63, v27
	v_dot8c_i32_i4_e32 v109, v63, v31
	s_nop 2
	v_lshl_add_u32 v110, v108, 4, v109
	s_nop 1
	v_add_u32_dpp v110, v110, v110 quad_perm:[1,0,3,2] row_mask:0xf bank_mask:0xf
	s_nop 1
	v_add_u32_dpp v110, v110, v110 quad_perm:[2,3,0,1] row_mask:0xf bank_mask:0xf
	s_nop 1
	v_add_u32_dpp v110, v110, v110 row_half_mirror row_mask:0xf bank_mask:0xf
	s_nop 1
	v_add_u32_dpp v110, v110, v110 row_mirror row_mask:0xf bank_mask:0xf
	s_mov_b64 exec, s[52:53]
	global_store_dword v106, v110, s[48:49]
	s_mov_b64 exec, -1
	s_add_i32 s58, s58, 1
	s_cmp_ge_u32 s58, s57
	s_cbranch_scc1 .Lgu_tnext
	s_waitcnt lgkmcnt(0)
	ds_read_b32 v117, v101
	v_cmp_gt_u32_e64 s[52:53], s59, v99
	v_add_u32_e32 v101, 16, v101
	s_sub_i32 s59, s59, 4
	s_max_i32 s59, s59, 0
	v_cndmask_b32_e64 v103, 0, v116, s[52:53]
	v_and_or_b32 v104, v103, s67, v96
	v_and_b32_e32 v106, 0x3ff, v103
	s_and_b64 s[52:53], s[52:53], s[8:9]
	global_load_dwordx4 v[48:51], v104, s[34:35]
	global_load_dwordx4 v[52:55], v104, s[34:35] offset:256
	global_load_dwordx4 v[56:59], v104, s[34:35] offset:512
	global_load_dwordx4 v[60:63], v104, s[34:35] offset:768
	s_waitcnt vmcnt(8)
	v_mov_b32_e32 v108, 0
	v_mov_b32_e32 v109, 0
	s_nop 1
	v_dot8c_i32_i4_e32 v108, v144, v0
	v_dot8c_i32_i4_e32 v109, v144, v4
	v_dot8c_i32_i4_e32 v108, v145, v1
	v_dot8c_i32_i4_e32 v109, v145, v5
	v_dot8c_i32_i4_e32 v108, v146, v2
	v_dot8c_i32_i4_e32 v109, v146, v6
	v_dot8c_i32_i4_e32 v108, v147, v3
	v_dot8c_i32_i4_e32 v109, v147, v7
	v_dot8c_i32_i4_e32 v108, v148, v8
	v_dot8c_i32_i4_e32 v109, v148, v12
	v_dot8c_i32_i4_e32 v108, v149, v9
	v_dot8c_i32_i4_e32 v109, v149, v13
	v_dot8c_i32_i4_e32 v108, v150, v10
	v_dot8c_i32_i4_e32 v109, v150, v14
	v_dot8c_i32_i4_e32 v108, v151, v11
	v_dot8c_i32_i4_e32 v109, v151, v15
	v_dot8c_i32_i4_e32 v108, v152, v16
	v_dot8c_i32_i4_e32 v109, v152, v20
	v_dot8c_i32_i4_e32 v108, v153, v17
	v_dot8c_i32_i4_e32 v109, v153, v21
	v_dot8c_i32_i4_e32 v108, v154, v18
	v_dot8c_i32_i4_e32 v109, v154, v22
	v_dot8c_i32_i4_e32 v108, v155, v19
	v_dot8c_i32_i4_e32 v109, v155, v23
	v_dot8c_i32_i4_e32 v108, v156, v24
	v_dot8c_i32_i4_e32 v109, v156, v28
	v_dot8c_i32_i4_e32 v108, v157, v25
	v_dot8c_i32_i4_e32 v109, v157, v29
	v_dot8c_i32_i4_e32 v108, v158, v26
	v_dot8c_i32_i4_e32 v109, v158, v30
	v_dot8c_i32_i4_e32 v108, v159, v27
	v_dot8c_i32_i4_e32 v109, v159, v31
	s_nop 2
	v_lshl_add_u32 v110, v108, 4, v109
	s_nop 1
	v_add_u32_dpp v110, v110, v110 quad_perm:[1,0,3,2] row_mask:0xf bank_mask:0xf
	s_nop 1
	v_add_u32_dpp v110, v110, v110 quad_perm:[2,3,0,1] row_mask:0xf bank_mask:0xf
	s_nop 1
	v_add_u32_dpp v110, v110, v110 row_half_mirror row_mask:0xf bank_mask:0xf
	s_nop 1
	v_add_u32_dpp v110, v110, v110 row_mirror row_mask:0xf bank_mask:0xf
	s_mov_b64 exec, s[54:55]
	global_store_dword v107, v110, s[48:49]
	s_mov_b64 exec, -1
	s_add_i32 s58, s58, 1
	s_cmp_lt_u32 s58, s57
	s_cbranch_scc1 .Lgu_gloop
